# attention: L2 touch of the K/V tile two steps ahead (one cache line per lane, kept in flight across the step)
# speedup vs baseline: 1.0029x; 1.0009x over previous
; __device__ __forceinline__ void attn_unit(const TI ti, CArgs& a, int b, int hd, int qrow0, int st_lo, int st_hi, float mfix, float lam, float lam_init, const float* subg, unsigned char* ldsg) {
;     ...
;         if (st + 1 < st_hi) ATT_STORE(bi ^ 1);
;         __syncthreads();
.LBB0_351:
	s_or_b64 exec, exec, s[4:5]
	s_add_i32 s17, s17, 1
	s_setprio 0
	s_xor_b32 s4, s48, 1
	s_mul_i32 s4, s4, 0x8c00
	s_add_i32 s4, s4, 0
	v_add_u32_e32 v82, s4, v147
	v_add_u32_e32 v83, v82, v155
	v_add_u32_e32 v82, v82, v156
	s_add_i32 s37, s37, 64
	s_add_i32 s39, s39, 64
	s_waitcnt vmcnt(4)
	ds_write_b128 v83, v[122:125]
	s_waitcnt vmcnt(3)
	ds_write_b128 v82, v[126:129]
	v_add3_u32 v82, s4, v157, v158
	s_cmp_eq_u32 s17, 35
	s_waitcnt vmcnt(2)
	ds_write_b16 v82, v118 offset:17408
	ds_write_b16_d16_hi v82, v118 offset:17552
	s_waitcnt vmcnt(1)
	ds_write_b16 v82, v114 offset:18560
	ds_write_b16_d16_hi v82, v114 offset:18704
	ds_write_b16 v82, v119 offset:17696
	ds_write_b16_d16_hi v82, v119 offset:17840
	ds_write_b16 v82, v115 offset:18848
	ds_write_b16_d16_hi v82, v115 offset:18992
	ds_write_b16 v82, v120 offset:17984
	ds_write_b16_d16_hi v82, v120 offset:18128
	ds_write_b16 v82, v116 offset:19136
	ds_write_b16_d16_hi v82, v116 offset:19280
	ds_write_b16 v82, v121 offset:18272
	ds_write_b16_d16_hi v82, v121 offset:18416
	ds_write_b16 v82, v117 offset:19424
	ds_write_b16_d16_hi v82, v117 offset:19568
	s_waitcnt lgkmcnt(0)
	s_barrier
	s_cbranch_scc1 .LBB0_356
; #define LAS __attribute__((address_space(3)))
; #define ATT_QK(SX, sub) do { __builtin_amdgcn_s_setprio(1); _Pragma("unroll") for (int ks = 0; ks < 4; ++ks) { \
;             const bf16x8 kf = *(LAS const bf16x8*)(Bb + KOFF + ((sub) * 32 + r) * 272 + (c * 64 + 16 * ks + 8 * h) * 2); SX = MFMA32(kf, qf[ks], SX); } __builtin_amdgcn_s_setprio(0); } while (0)
; #define ATT_SOFT(SX, P0, P1) do { float p[16]; _Pragma("unroll") for (int i = 0; i < 16; ++i) { p[i] = __builtin_amdgcn_exp2f(SX[i]); lsum += p[i]; } \
;             P0 = pk8f(p[0], p[1], p[2], p[3], p[4], p[5], p[6], p[7]); P1 = pk8f(p[8], p[9], p[10], p[11], p[12], p[13], p[14], p[15]); } while (0)
; #define ATT_PV(sub, P0, P1) do { __builtin_amdgcn_s_setprio(1); _Pragma("unroll") for (int et = 0; et < 4; ++et) { _Pragma("unroll") for (int s = 0; s < 2; ++s) { \
;             const bf16x8 vf = *(LAS const bf16x8*)(Bb + VOFF + (et * 32 + r) * 144 + ((sub) * 32 + 16 * s + 8 * h) * 2); O[et] = MFMA32(vf, s ? P1 : P0, O[et]); } } __builtin_amdgcn_s_setprio(0); } while (0)
; __device__ __forceinline__ void attn_unit(const TI ti, CArgs& a, int b, int hd, int qrow0, int st_lo, int st_hi, float mfix, float lam, float lam_init, const float* subg, unsigned char* ldsg) {
;     ...
;     ATT_LOAD(st_lo); ATT_STORE(0);
;     __syncthreads();
;     for (int st = st_lo; st < st_hi; ++st) {
;         const int bi = (st - st_lo) & 1;
;         if (st + 1 < st_hi) ATT_LOAD(st + 1);
;         LAS const unsigned char* Bb = L + bi * BUFB;
;         f32x16 Sx0, Sx1; bf16x8 pa0, pa1, pc0, pc1;
; #pragma unroll
;         for (int i = 0; i < 16; ++i) { Sx0[i] = -mfix; Sx1[i] = -mfix; }
;     ...
;         if (w < 4) {
;             ATT_QK(Sx0, 0); ATT_QK(Sx1, 1);
;             __builtin_amdgcn_sched_barrier(0);
;             ATT_SOFT(Sx0, pa0, pa1); ATT_PV(0, pa0, pa1);
;             ATT_SOFT(Sx1, pc0, pc1); ATT_PV(1, pc0, pc1);
;         } else {
;             ATT_QK(Sx0, 0);
;             __builtin_amdgcn_sched_barrier(0);
;             ATT_SOFT(Sx0, pa0, pa1);
;             __builtin_amdgcn_sched_barrier(0);
;             ATT_QK(Sx1, 1); ATT_PV(0, pa0, pa1);
;             __builtin_amdgcn_sched_barrier(0);
;             ATT_SOFT(Sx1, pc0, pc1); ATT_PV(1, pc0, pc1);
;         }
.LBB0_352:
	s_and_b32 s48, s17, 1
	s_cmp_lt_u32 s17, 31
	s_cselect_b32 s4, s39, s37
	s_ashr_i32 s5, s4, 31
	s_lshl_b64 s[4:5], s[4:5], 11
	s_add_u32 s33, s27, s4
	s_addc_u32 s36, s34, s5
	v_mov_b32_e32 v82, s33
	v_mov_b32_e32 v83, s36
	s_add_u32 s4, s18, s4
	s_addc_u32 s5, s35, s5
	v_lshl_add_u64 v[82:83], v[140:141], 1, v[82:83]
	v_mov_b32_e32 v84, s4
	v_mov_b32_e32 v85, s5
	v_add_co_u32_e32 v86, vcc, s79, v82
	s_mul_i32 s4, s48, 0x8c00
	s_nop 0
	v_addc_co_u32_e32 v87, vcc, 0, v83, vcc
	global_load_dwordx4 v[122:125], v[82:83], off
	global_load_dwordx4 v[126:129], v[86:87], off
	v_lshl_add_u64 v[82:83], v[142:143], 1, v[84:85]
	global_load_dwordx4 v[118:121], v[82:83], off
	global_load_dwordx4 v[114:117], v[82:83], off offset:16
	s_cmp_lt_u32 s17, 30
	s_cselect_b32 s98, s39, s37
	s_cmp_lt_u32 s17, 34
	s_cselect_b32 s99, 64, 0
	s_add_i32 s98, s98, s99
	s_ashr_i32 s99, s98, 31
	s_lshl_b64 s[98:99], s[98:99], 11
	s_add_u32 s98, s27, s98
	s_addc_u32 s99, s34, s99
	v_lshrrev_b32_e32 v249, 3, v178
	v_and_b32_e32 v250, 4, v178
	v_and_b32_e32 v251, 3, v178
	v_lshlrev_b32_e32 v249, 11, v249
	v_mul_u32_u24_e32 v250, 0x900000, v250
	v_lshl_add_u32 v249, v251, 6, v249
	v_add_u32_e32 v249, v249, v250
	global_load_dword v252, v249, s[98:99]
	s_add_i32 s4, s4, 0
	s_setprio 1
	v_add_u32_e32 v82, s4, v160
	v_add_u32_e32 v151, v82, v161
	ds_read_b128 v[130:133], v151
	v_add3_u32 v150, s4, v144, v162
	s_and_saveexec_b64 s[4:5], s[40:41]
	s_xor_b64 s[4:5], exec, s[4:5]
	s_cbranch_execz .LBB0_354
	ds_read_b128 v[182:185], v151 offset:32
	ds_read_b128 v[198:201], v151 offset:64
	ds_read_b128 v[202:205], v151 offset:96
	ds_read_b128 v[206:209], v151 offset:8704
	ds_read_b128 v[210:213], v151 offset:8736
	ds_read_b128 v[236:239], v151 offset:8768
	ds_read_b128 v[240:243], v151 offset:8800
	s_setprio 1
	s_waitcnt lgkmcnt(7)
	v_mfma_f32_32x32x16_bf16 v[82:97], v[130:133], v[110:113], v[2:17]
	s_waitcnt lgkmcnt(6)
	v_mfma_f32_32x32x16_bf16 v[82:97], v[182:185], v[106:109], v[82:97]
	s_waitcnt lgkmcnt(5)
	v_mfma_f32_32x32x16_bf16 v[82:97], v[198:201], v[102:105], v[82:97]
	s_waitcnt lgkmcnt(4)
	v_mfma_f32_32x32x16_bf16 v[82:97], v[202:205], v[98:101], v[82:97]
	ds_read_b128 v[130:133], v150 offset:17408
	ds_read_b128 v[182:185], v150 offset:17440
	ds_read_b128 v[198:201], v150 offset:22016
	ds_read_b128 v[202:205], v150 offset:22048
	s_waitcnt lgkmcnt(7)
	v_mfma_f32_32x32x16_bf16 v[220:235], v[206:209], v[110:113], v[2:17]
	s_waitcnt lgkmcnt(6)
	v_mfma_f32_32x32x16_bf16 v[220:235], v[210:213], v[106:109], v[220:235]
	s_waitcnt lgkmcnt(5)
	v_mfma_f32_32x32x16_bf16 v[220:235], v[236:239], v[102:105], v[220:235]
	s_waitcnt lgkmcnt(4)
	v_mfma_f32_32x32x16_bf16 v[220:235], v[240:243], v[98:101], v[220:235]
	ds_read_b128 v[206:209], v150 offset:26624
	ds_read_b128 v[210:213], v150 offset:26656
	ds_read_b128 v[236:239], v150 offset:31232
	ds_read_b128 v[240:243], v150 offset:31264
	s_setprio 0
	v_exp_f32_e32 v169, v82
	v_exp_f32_e32 v170, v83
	v_exp_f32_e32 v171, v84
	v_exp_f32_e32 v174, v85
	v_exp_f32_e32 v175, v86
	v_exp_f32_e32 v176, v87
	v_exp_f32_e32 v177, v88
	v_exp_f32_e32 v179, v89
	v_exp_f32_e32 v90, v90
	v_exp_f32_e32 v91, v91
	v_exp_f32_e32 v92, v92
	v_exp_f32_e32 v93, v93
	v_exp_f32_e32 v94, v94
	v_exp_f32_e32 v95, v95
	v_exp_f32_e32 v96, v96
	v_exp_f32_e32 v97, v97
	v_cvt_pk_bf16_f32 v82, v169, v170
	v_cvt_pk_bf16_f32 v83, v171, v174
	v_cvt_pk_bf16_f32 v84, v175, v176
	v_cvt_pk_bf16_f32 v85, v177, v179
	v_cvt_pk_bf16_f32 v86, v90, v91
	v_cvt_pk_bf16_f32 v87, v92, v93
	v_cvt_pk_bf16_f32 v88, v94, v95
	v_cvt_pk_bf16_f32 v89, v96, v97
	s_setprio 1
	s_waitcnt lgkmcnt(7)
	v_mfma_f32_32x32x16_bf16 v[18:33], v[130:133], v[82:85], v[18:33]
	v_add_f32_e32 v0, v169, v0
	v_add_f32_e32 v0, v170, v0
	s_waitcnt lgkmcnt(6)
	v_mfma_f32_32x32x16_bf16 v[18:33], v[182:185], v[86:89], v[18:33]
	v_add_f32_e32 v0, v171, v0
	v_add_f32_e32 v0, v174, v0
	ds_read_b128 v[130:133], v150 offset:17472
	ds_read_b128 v[182:185], v150 offset:17504
	s_waitcnt lgkmcnt(7)
	v_mfma_f32_32x32x16_bf16 v[34:49], v[198:201], v[82:85], v[34:49]
	v_add_f32_e32 v0, v175, v0
	v_add_f32_e32 v0, v176, v0
	s_waitcnt lgkmcnt(6)
	v_mfma_f32_32x32x16_bf16 v[34:49], v[202:205], v[86:89], v[34:49]
	v_add_f32_e32 v0, v177, v0
	v_add_f32_e32 v0, v179, v0
	ds_read_b128 v[198:201], v150 offset:22080
	ds_read_b128 v[202:205], v150 offset:22112
	s_waitcnt lgkmcnt(7)
	v_mfma_f32_32x32x16_bf16 v[66:81], v[206:209], v[82:85], v[66:81]
	v_add_f32_e32 v0, v90, v0
	v_add_f32_e32 v0, v91, v0
	s_waitcnt lgkmcnt(6)
	v_mfma_f32_32x32x16_bf16 v[66:81], v[210:213], v[86:89], v[66:81]
	v_add_f32_e32 v0, v92, v0
	v_add_f32_e32 v0, v93, v0
	ds_read_b128 v[206:209], v150 offset:26688
	ds_read_b128 v[210:213], v150 offset:26720
	s_waitcnt lgkmcnt(7)
	v_mfma_f32_32x32x16_bf16 v[50:65], v[236:239], v[82:85], v[50:65]
	v_add_f32_e32 v0, v94, v0
	v_add_f32_e32 v0, v95, v0
	s_waitcnt lgkmcnt(6)
	v_mfma_f32_32x32x16_bf16 v[50:65], v[240:243], v[86:89], v[50:65]
	v_add_f32_e32 v0, v96, v0
	v_add_f32_e32 v0, v97, v0
	ds_read_b128 v[236:239], v150 offset:31296
	ds_read_b128 v[240:243], v150 offset:31328
	s_setprio 0
	v_exp_f32_e32 v181, v220
	v_exp_f32_e32 v197, v221
	v_exp_f32_e32 v214, v222
	v_exp_f32_e32 v244, v223
	v_exp_f32_e32 v245, v224
	v_exp_f32_e32 v246, v225
	v_exp_f32_e32 v247, v226
	v_exp_f32_e32 v248, v227
	v_exp_f32_e32 v228, v228
	v_exp_f32_e32 v229, v229
	v_exp_f32_e32 v230, v230
	v_exp_f32_e32 v231, v231
	v_exp_f32_e32 v232, v232
	v_exp_f32_e32 v233, v233
	v_exp_f32_e32 v234, v234
	v_exp_f32_e32 v235, v235
	v_cvt_pk_bf16_f32 v220, v181, v197
	v_cvt_pk_bf16_f32 v221, v214, v244
	v_cvt_pk_bf16_f32 v222, v245, v246
	v_cvt_pk_bf16_f32 v223, v247, v248
	v_cvt_pk_bf16_f32 v224, v228, v229
	v_cvt_pk_bf16_f32 v225, v230, v231
	v_cvt_pk_bf16_f32 v226, v232, v233
	v_cvt_pk_bf16_f32 v227, v234, v235
	s_setprio 1
	s_waitcnt lgkmcnt(7)
	v_mfma_f32_32x32x16_bf16 v[18:33], v[130:133], v[220:223], v[18:33]
	v_add_f32_e32 v0, v181, v0
	v_add_f32_e32 v0, v197, v0
	s_waitcnt lgkmcnt(6)
	v_mfma_f32_32x32x16_bf16 v[18:33], v[182:185], v[224:227], v[18:33]
	v_add_f32_e32 v0, v214, v0
	v_add_f32_e32 v0, v244, v0
	s_waitcnt lgkmcnt(5)
	v_mfma_f32_32x32x16_bf16 v[34:49], v[198:201], v[220:223], v[34:49]
	v_add_f32_e32 v0, v245, v0
	v_add_f32_e32 v0, v246, v0
	s_waitcnt lgkmcnt(4)
	v_mfma_f32_32x32x16_bf16 v[34:49], v[202:205], v[224:227], v[34:49]
	v_add_f32_e32 v0, v247, v0
	v_add_f32_e32 v0, v248, v0
	s_waitcnt lgkmcnt(3)
	v_mfma_f32_32x32x16_bf16 v[66:81], v[206:209], v[220:223], v[66:81]
	v_add_f32_e32 v0, v228, v0
	v_add_f32_e32 v0, v229, v0
	s_waitcnt lgkmcnt(2)
	v_mfma_f32_32x32x16_bf16 v[66:81], v[210:213], v[224:227], v[66:81]
	v_add_f32_e32 v0, v230, v0
	v_add_f32_e32 v0, v231, v0
	s_waitcnt lgkmcnt(1)
	v_mfma_f32_32x32x16_bf16 v[50:65], v[236:239], v[220:223], v[50:65]
	v_add_f32_e32 v0, v232, v0
	v_add_f32_e32 v0, v233, v0
	s_waitcnt lgkmcnt(0)
	v_mfma_f32_32x32x16_bf16 v[50:65], v[240:243], v[224:227], v[50:65]
	v_add_f32_e32 v0, v234, v0
	v_add_f32_e32 v0, v235, v0
